# cross-attention q projection (phase F) also walks row panels in reverse; on top of reversed H and down GEMM + staggered GEMM starts
# baseline (speedup 1.0000x reference)
;     __device__ bool next(int i, Unit& u) const {
;         const long L = (long)i * G + c; if (L >= nwg) return false;
;         int wgid = (int)L; { const int q = nwg / NXCD, r = nwg % NXCD, xcd = wgid % NXCD, off = wgid / NXCD; wgid = (xcd < r ? xcd * (q + 1) : r * (q + 1) + (xcd - r) * q) + off; }
;         const int nig = WGM * nN, gid = wgid / nig, fm = gid * WGM, gsz = (nM - fm) < WGM ? (nM - fm) : WGM;
;         u.pm = fm + ((wgid % nig) % gsz); u.pn = (wgid % nig) / gsz; return true;
;     }
; __global__ void __launch_bounds__(NWAVES * 64, 2) mega_fwd(Args args) {
;     ...
;         { pg8::Gemm g{XB, Wcq_t, NTOK, CWID, DM, DM, 0}; pg8::StaticOrder S; S.init(NTOK, CWID, G, bx);
;           pg8::EpiB E{QC, CWID, 0, ss1, 0};
;           _Pragma("unroll 1") for (int rep = 0; rep <= DUP_F; ++rep)
;           pg8::gemm_phase<pg8::EpiB, pg8::StaticOrder>(L, g, S, E); }
.LBB0_792:
	v_readlane_b32 s0, v248, 0
	v_readlane_b32 s2, v248, 2
	v_readlane_b32 s1, v248, 1
	v_readlane_b32 s3, v248, 3
	s_cmp_lt_i32 s2, 12
	s_cselect_b64 s[0:1], -1, 0
	s_cmp_gt_i32 s3, 11
	s_cselect_b64 s[2:3], -1, 0
	s_and_b64 s[2:3], s[0:1], s[2:3]
	s_and_b64 vcc, exec, s[2:3]
	s_cbranch_vccz .LBB0_852
	v_readlane_b32 s2, v248, 4
	v_readlane_b32 s3, v248, 5
	v_mov_b32_e32 v0, v214
	s_load_dwordx2 s[6:7], s[2:3], 0xb0
	v_readlane_b32 s2, v248, 8
	s_cmpk_lt_i32 s2, 0x180
	s_cselect_b64 s[2:3], -1, 0
	v_mov_b32_e32 v13, v214
	s_and_b64 vcc, exec, s[2:3]
	v_readfirstlane_b32 s16, v13
	s_cbranch_vccz .LBB0_795
	v_readlane_b32 s4, v248, 15
	v_readlane_b32 s5, v248, 16
	s_and_b64 s[4:5], s[4:5], exec
	s_cselect_b32 s4, 49, 48
	v_readlane_b32 s5, v247, 37
	s_mul_i32 s4, s5, s4
	v_readlane_b32 s5, v248, 13
	s_add_i32 s4, s4, s5
	s_ashr_i32 s5, s4, 31
	s_lshr_b32 s5, s5, 28
	s_add_i32 s5, s4, s5
	s_ashr_i32 s8, s5, 4
	s_and_b32 s5, s5, 0xfff0
	s_sub_i32 s4, s4, s5
	s_bfe_i32 s5, s4, 0x80000
	s_bfe_u32 s5, s5, 0x3000c
	s_add_i32 s5, s4, s5
	s_bfe_i32 s9, s5, 0x80000
	s_and_b32 s5, s5, 0xf8
	s_sub_i32 s4, s4, s5
	s_lshl_b32 s8, s8, 3
	s_sext_i32_i16 s9, s9
	s_sext_i32_i8 s4, s4
	s_add_i32 s4, s8, s4
	s_ashr_i32 s26, s9, 3
	s_sub_i32 s4, 0xbf, s4

;     ...
;         const bool has_next = S.next(ui + 1, nxt);
;         const char* nA = has_next ? (const char*)g.A + (size_t)nxt.pm * tstepA : cA; const char* nB = has_next ? (const char*)g.Bt + (size_t)nxt.pn * tstepB : cB;
;     ...
; #pragma unroll
;         for (int a = 0; a < 2; ++a)
; #pragma unroll
;             for (int b = 0; b < 2; ++b)
; #pragma unroll
;                 for (int m = 0; m < 4; ++m)
; #pragma unroll
;                     for (int n = 0; n < 2; ++n) acc[a][b][m][n] = (f32x4){0.f, 0.f, 0.f, 0.f};
;         cur = nxt; cA = nA; cB = nB; ++ui;
.LBB0_803:
	s_sub_i32 s20, 0xbf, s20
	s_ashr_i32 s21, s20, 31
	s_lshl_b64 s[22:23], s[20:21], 20
	s_add_u32 s22, s35, s22
	s_addc_u32 s23, s38, s23
	s_and_b64 s[24:25], s[2:3], exec
	s_cselect_b32 s5, s23, s29
	s_cselect_b32 s21, s22, s28
	s_ashr_i32 s19, s18, 31
	s_lshl_b64 s[24:25], s[18:19], 20
	s_add_u32 s24, s33, s24
	s_addc_u32 s25, s34, s25
	s_and_b64 s[36:37], s[2:3], exec
	s_cselect_b32 s19, s25, s31
	s_cselect_b32 s48, s24, s30
	s_add_u32 s28, s28, 0x80080
	s_addc_u32 s29, s29, 0
	s_add_u32 s49, s30, 0x100
	v_mov_b32_e32 v0, 0
	s_addc_u32 s50, s31, 0
	s_mov_b32 s51, -2
	v_mov_b32_e32 v1, v0
	v_mov_b32_e32 v2, v0
	v_mov_b32_e32 v3, v0
	v_mov_b32_e32 v4, v0
	v_mov_b32_e32 v5, v0
	v_mov_b32_e32 v6, v0
	v_mov_b32_e32 v7, v0
	v_mov_b32_e32 v16, v0
	v_mov_b32_e32 v17, v0
	v_mov_b32_e32 v18, v0
	v_mov_b32_e32 v19, v0
	v_mov_b32_e32 v20, v0
	v_mov_b32_e32 v21, v0
	v_mov_b32_e32 v22, v0
	v_mov_b32_e32 v23, v0
	v_mov_b32_e32 v32, v0
	v_mov_b32_e32 v33, v0
	v_mov_b32_e32 v34, v0
	v_mov_b32_e32 v35, v0
	v_mov_b32_e32 v36, v0
	v_mov_b32_e32 v37, v0
	v_mov_b32_e32 v38, v0
	v_mov_b32_e32 v39, v0
	v_mov_b32_e32 v48, v0
	v_mov_b32_e32 v49, v0
	v_mov_b32_e32 v50, v0
	v_mov_b32_e32 v51, v0
	v_mov_b32_e32 v52, v0
	v_mov_b32_e32 v53, v0
	v_mov_b32_e32 v54, v0
	v_mov_b32_e32 v55, v0
	v_mov_b32_e32 v8, v0
	v_mov_b32_e32 v9, v0
	v_mov_b32_e32 v10, v0
	v_mov_b32_e32 v11, v0
	v_mov_b32_e32 v12, v0
	v_mov_b32_e32 v13, v0
	v_mov_b32_e32 v14, v0
	v_mov_b32_e32 v15, v0
	v_mov_b32_e32 v24, v0
	v_mov_b32_e32 v25, v0
	v_mov_b32_e32 v26, v0
	v_mov_b32_e32 v27, v0
	v_mov_b32_e32 v28, v0
	v_mov_b32_e32 v29, v0
	v_mov_b32_e32 v30, v0
	v_mov_b32_e32 v31, v0
	v_mov_b32_e32 v40, v0
	v_mov_b32_e32 v41, v0
	v_mov_b32_e32 v42, v0
	v_mov_b32_e32 v43, v0
	v_mov_b32_e32 v44, v0
	v_mov_b32_e32 v45, v0
	v_mov_b32_e32 v46, v0
	v_mov_b32_e32 v47, v0
	v_mov_b32_e32 v56, v0
	v_mov_b32_e32 v57, v0
	v_mov_b32_e32 v58, v0
	v_mov_b32_e32 v59, v0
	v_mov_b32_e32 v60, v0
	v_mov_b32_e32 v61, v0
	v_mov_b32_e32 v62, v0
	v_mov_b32_e32 v63, v0
	v_mov_b32_e32 v64, v0
	v_mov_b32_e32 v65, v0
	v_mov_b32_e32 v66, v0
	v_mov_b32_e32 v67, v0
	v_mov_b32_e32 v68, v0
	v_mov_b32_e32 v69, v0
	v_mov_b32_e32 v70, v0
	v_mov_b32_e32 v71, v0
	v_mov_b32_e32 v80, v0
	v_mov_b32_e32 v81, v0
	v_mov_b32_e32 v82, v0
	v_mov_b32_e32 v83, v0
	v_mov_b32_e32 v84, v0
	v_mov_b32_e32 v85, v0
	v_mov_b32_e32 v86, v0
	v_mov_b32_e32 v87, v0
	v_mov_b32_e32 v96, v0
	v_mov_b32_e32 v97, v0
	v_mov_b32_e32 v98, v0
	v_mov_b32_e32 v99, v0
	v_mov_b32_e32 v100, v0
	v_mov_b32_e32 v101, v0
	v_mov_b32_e32 v102, v0
	v_mov_b32_e32 v103, v0
	v_mov_b32_e32 v112, v0
	v_mov_b32_e32 v113, v0
	v_mov_b32_e32 v114, v0
	v_mov_b32_e32 v115, v0
	v_mov_b32_e32 v116, v0
	v_mov_b32_e32 v117, v0
	v_mov_b32_e32 v118, v0
	v_mov_b32_e32 v119, v0
	v_mov_b32_e32 v72, v0
	v_mov_b32_e32 v73, v0
	v_mov_b32_e32 v74, v0
	v_mov_b32_e32 v75, v0
	v_mov_b32_e32 v76, v0
	v_mov_b32_e32 v77, v0
	v_mov_b32_e32 v78, v0
	v_mov_b32_e32 v79, v0
	v_mov_b32_e32 v88, v0
	v_mov_b32_e32 v89, v0
	v_mov_b32_e32 v90, v0
	v_mov_b32_e32 v91, v0
	v_mov_b32_e32 v92, v0
	v_mov_b32_e32 v93, v0
	v_mov_b32_e32 v94, v0
	v_mov_b32_e32 v95, v0
	v_mov_b32_e32 v104, v0
	v_mov_b32_e32 v105, v0
	v_mov_b32_e32 v106, v0
	v_mov_b32_e32 v107, v0
	v_mov_b32_e32 v108, v0
	v_mov_b32_e32 v109, v0
	v_mov_b32_e32 v110, v0
	v_mov_b32_e32 v111, v0
	v_mov_b32_e32 v120, v0
	v_mov_b32_e32 v121, v0
	v_mov_b32_e32 v122, v0
	v_mov_b32_e32 v123, v0
	v_mov_b32_e32 v124, v0
	v_mov_b32_e32 v125, v0
	v_mov_b32_e32 v126, v0
	v_mov_b32_e32 v127, v0
